# speedup vs baseline: 1.0077x; 1.0038x over previous
.LBB0_538:
	s_waitcnt vmcnt(0)
	s_add_u32 s22, s20, 0xb8
	s_addc_u32 s23, s21, 0
	s_add_u32 s24, s20, 0x88
	s_addc_u32 s25, s21, 0
	s_add_u32 s26, s20, 0x48
	s_addc_u32 s27, s21, 0
	s_add_u32 s28, s20, 40
	s_addc_u32 s29, s21, 0
	s_add_i32 s39, s30, 0xffffd800
	s_mov_b32 s33, 0
	s_branch .LBB0_540
.LBB0_539:
	v_mad_i64_i32 v[6:7], s[4:5], s8, v6, 0
	s_lshl_b32 s4, s12, 6
	v_lshl_add_u64 v[6:7], v[6:7], 1, s[6:7]
	s_ashr_i32 s5, s4, 31
	v_lshl_add_u64 v[6:7], s[4:5], 1, v[6:7]
	v_lshlrev_b32_e32 v8, 1, v1
	v_mov_b32_e32 v9, v0
	v_lshl_add_u64 v[6:7], v[6:7], 0, v[8:9]
	global_store_dwordx4 v[6:7], v[2:5], off
	s_xor_b32 s33, s33, 1
	s_andn2_b64 vcc, exec, s[30:31]
	s_mov_b32 s39, s38
	s_waitcnt vmcnt(1)
	v_mov_b32_e32 v2, v10
	v_mov_b32_e32 v3, v11
	v_mov_b32_e32 v4, v12
	v_mov_b32_e32 v5, v13
	v_mov_b32_e32 v6, v14
	v_mov_b32_e32 v7, v15
	v_mov_b32_e32 v8, v16
	v_mov_b32_e32 v9, v17
	v_mul_f32_e32 v18, v55, v22
	v_mul_f32_e32 v20, v55, v23
	s_cbranch_vccz .LBB0_623
.LBB0_540:
	v_mov_b32_e32 v55, 1.0
	s_add_i32 s38, s73, s39
	s_add_i32 s40, s38, 0x2800
	s_cmpk_gt_i32 s40, 0x28ff
	s_cselect_b64 s[30:31], -1, 0
	s_and_b64 vcc, exec, s[30:31]
	s_cbranch_vccnz .LBB0_561
	s_cmpk_gt_i32 s40, 0x20ff
	s_mov_b64 s[8:9], -1
	s_cbranch_scc0 .LBB0_554
	s_cmpk_gt_u32 s40, 0x23ff
	s_mov_b64 s[12:13], -1
	s_cbranch_scc0 .LBB0_551
	s_cmpk_gt_u32 s40, 0x24ff
	s_cbranch_scc0 .LBB0_548
	s_cmpk_gt_u32 s40, 0x27ff
	s_mov_b64 s[4:5], -1
	s_cbranch_scc0 .LBB0_546
	s_lshr_b32 s36, s38, 4
	s_and_b32 s37, s40, 15
	s_mov_b64 s[4:5], 0

.LBB0_599:
	v_readlane_b32 s8, v254, 39
	v_mbcnt_lo_u32_b32 v12, -1, 0
	v_mbcnt_hi_u32_b32 v12, -1, v12
	s_nop 1
	v_add_u32_e32 v1, s8, v12
	v_ashrrev_i32_e32 v1, 4, v1
	v_lshl_add_u32 v19, s36, 6, v1
	v_ashrrev_i32_e32 v10, 31, v19
	v_add_u32_e32 v1, 32, v19
	v_mul_lo_u32 v13, s4, v10
	v_mul_lo_u32 v14, s5, v19
	v_mad_u64_u32 v[10:11], s[8:9], s4, v19, 0
	v_add3_u32 v11, v11, v13, v14
	v_ashrrev_i32_e32 v14, 31, v1
	s_lshl_b32 s8, s37, 6
	v_mul_lo_u32 v16, s4, v14
	v_mul_lo_u32 v17, s5, v1
	v_mad_u64_u32 v[14:15], s[4:5], s4, v1, 0
	s_ashr_i32 s9, s8, 31
	v_add3_u32 v15, v15, v16, v17
	s_waitcnt lgkmcnt(0)
	v_lshl_add_u64 v[10:11], v[10:11], 2, s[14:15]
	s_lshl_b64 s[8:9], s[8:9], 2
	v_lshlrev_b32_e32 v12, 4, v12
	v_lshl_add_u64 v[14:15], v[14:15], 2, s[14:15]
	v_lshl_add_u64 v[10:11], v[10:11], 0, s[8:9]
	v_and_b32_e32 v12, 0xf0, v12
	v_mov_b32_e32 v13, v0
	v_lshl_add_u64 v[14:15], v[14:15], 0, s[8:9]
	v_lshl_add_u64 v[10:11], v[10:11], 0, v[12:13]
	v_lshl_add_u64 v[14:15], v[14:15], 0, v[12:13]
	global_load_dwordx4 v[10:13], v[10:11], off
	s_nop 0
	global_load_dwordx4 v[14:17], v[14:15], off
	s_cmp_eq_u64 s[10:11], 0
	s_cbranch_scc1 .LBB0_601
	v_and_b32_e32 v22, s7, v19
	v_mov_b32_e32 v23, v0
	v_lshl_add_u64 v[22:23], v[22:23], 2, s[10:11]
	v_and_b32_e32 v24, s7, v1
	v_mov_b32_e32 v25, v0
	v_lshl_add_u64 v[24:25], v[24:25], 2, s[10:11]
	global_load_dword v23, v[22:23], off
	s_nop 0
	global_load_dword v22, v[24:25], off
	v_mov_b32_e32 v55, s6
	s_branch .LBB0_602

.LBB0_621:
	v_readlane_b32 s9, v254, 39
	v_mbcnt_lo_u32_b32 v1, -1, 0
	v_mbcnt_hi_u32_b32 v1, -1, v1
	s_movk_i32 s10, 0x104
	v_lshlrev_b32_e32 v24, 4, v1
	v_add_u32_e32 v19, s9, v1
	s_mul_i32 s9, s33, 0x4180
	v_ashrrev_i32_e32 v21, 4, v19
	s_add_i32 s9, s9, 0
	v_mul_lo_u32 v21, v21, s10
	v_and_b32_e32 v24, 0xf0, v24
	v_add3_u32 v21, s9, v21, v24
	v_pk_mul_f32 v[2:3], v[2:3], v[20:21] op_sel_hi:[1,0]
	ds_write2_b32 v21, v2, v3 offset1:1
	v_pk_mul_f32 v[2:3], v[4:5], v[20:21] op_sel_hi:[1,0]
	ds_write2_b32 v21, v2, v3 offset0:2 offset1:3
	v_add_u32_e32 v4, 0x2080, v21
	v_pk_mul_f32 v[2:3], v[6:7], v[18:19] op_sel_hi:[1,0]
	v_lshlrev_b32_e32 v1, 3, v1
	ds_write2_b32 v4, v2, v3 offset1:1
	v_add_u32_e32 v4, 0x2088, v21
	v_pk_mul_f32 v[2:3], v[8:9], v[18:19] op_sel_hi:[1,0]
	v_ashrrev_i32_e32 v18, 3, v19
	v_and_b32_e32 v1, 56, v1
	ds_write2_b32 v4, v2, v3 offset1:1
	v_mul_u32_u24_e32 v2, 0x104, v1
	v_lshlrev_b32_e32 v3, 2, v18
	v_add3_u32 v6, s9, v2, v3
	s_waitcnt lgkmcnt(0)
	s_barrier
	ds_read2_b32 v[2:3], v6 offset1:65
	ds_read2_b32 v[4:5], v6 offset0:130 offset1:195
	v_add_u32_e32 v8, 0x400, v6
	ds_read2_b32 v[6:7], v8 offset0:4 offset1:69
	ds_read2_b32 v[8:9], v8 offset0:134 offset1:199
	s_waitcnt lgkmcnt(3)
	v_cvt_pk_bf16_f32 v2, v2, v3
	s_waitcnt lgkmcnt(2)
	v_cvt_pk_bf16_f32 v3, v4, v5
	s_waitcnt lgkmcnt(1)
	v_cvt_pk_bf16_f32 v4, v6, v7
	v_lshl_add_u32 v6, s13, 6, v18
	s_and_b64 vcc, exec, s[4:5]
	s_waitcnt lgkmcnt(0)
	v_cvt_pk_bf16_f32 v5, v8, v9
	s_cbranch_vccnz .LBB0_539
	s_movk_i32 s4, 0xaff
	v_cmp_lt_i32_e32 vcc, s4, v6
	v_mov_b32_e32 v7, 0xfffff500
	v_mov_b32_e32 v8, 0x80
	v_cndmask_b32_e32 v7, 0, v7, vcc
	v_add_lshl_u32 v7, v7, v6, 1
	v_and_b32_e32 v7, 0xffffff00, v7
	v_cndmask_b32_e32 v8, 0, v8, vcc
	v_and_b32_e32 v6, 0x7f, v6
	v_or3_b32 v6, v8, v6, v7
	s_branch .LBB0_539
